# S5 carry moved from gate workgroups to the 32 thin workgroups that hold the cheap context attention units (bid Gthin-32..Gthin-1), on top of v030
# baseline (speedup 1.0000x reference)
; __global__ void __launch_bounds__(512, 2) mega_fwd(Args args) {
;     ...
;             { PH_BEGIN if (cb_ == 0 && bid < 32) { CARRY_BLOCK(bid) } },
.LBB0_868:
	s_sub_i32 s14, s92, 32
	s_max_i32 s14, s14, 0
	s_sub_i32 s14, s81, s14
	s_mov_b32 s0, s92
	s_waitcnt lgkmcnt(0)
	s_barrier
	s_mov_b32 s0, s93
	v_mbcnt_lo_u32_b32 v0, -1, 0
	v_mbcnt_hi_u32_b32 v0, -1, v0
	s_cmp_lt_u32 s14, 32
	v_lshl_or_b32 v0, s0, 6, v0
	v_mov_b32 v1, 0
	v_readlane_b32 s6, v254, 2
	v_add_u32_e32 v1, s79, v1
	ds_read_b32 v2, v1 offset:280
	ds_read_b32 v1, v1 offset:284
	s_cselect_b64 s[0:1], -1, 0
	v_readlane_b32 s7, v254, 3
	s_and_b64 s[0:1], s[6:7], s[0:1]
	v_readfirstlane_b32 s15, v0
	s_waitcnt lgkmcnt(1)
	v_readfirstlane_b32 s4, v2
	s_waitcnt lgkmcnt(0)
	v_readfirstlane_b32 s5, v1
	s_and_b64 vcc, exec, s[0:1]
	s_mov_b32 s80, 0x8000
	s_mov_b32 s97, 0xf800000
	s_movk_i32 s66, 0x1000
	s_movk_i32 s60, 0x4000
	s_mov_b64 s[28:29], 0x14a00000
	s_cbranch_vccz .LBB0_890
	v_cmp_eq_u32_e32 vcc, 0, v0
	s_barrier
	s_and_saveexec_b64 s[0:1], vcc
	s_cbranch_execz .LBB0_884
	v_readlane_b32 s6, v254, 49
	v_readlane_b32 s7, v254, 50
	s_lshl_b64 s[6:7], s[6:7], 2
	s_add_u32 s6, s4, s6
	s_addc_u32 s7, s5, s7
	v_mov_b32_e32 v1, 0x8000
	s_movk_i32 s8, 0x15f
	global_load_dword v1, v1, s[6:7] sc1
	s_add_u32 s6, s6, 0x8000
	s_addc_u32 s7, s7, 0
	s_waitcnt vmcnt(0)
	v_cmp_lt_u32_e32 vcc, s8, v1
	s_cbranch_vccnz .LBB0_883
	s_add_u32 s4, s4, 0x4200
	s_addc_u32 s5, s5, 0
	s_mov_b32 s16, 1
	s_branch .LBB0_873
